# up-projection: the next tile's last missing K-tile-1 piece is staged at the top of the epilogue (before its stores) and the next K loop's first three in-order vmcnt waits are skipped once, so the epil
# speedup vs baseline: 1.0005x; 1.0005x over previous
; #define PG8_STAGE(bufoff, gbase, voff) do { _Pragma("unroll") for (int _i = 0; _i < 2; ++_i) \
;         __builtin_amdgcn_global_load_lds((const unsigned*)((const char*)(gbase) + (voff)[_i]), (PG8_LAS unsigned*)(lds + (bufoff) + ldsw + _i * 8192), 16, 0, 0); } while (0)
; #define PG8_LDA(dst, b, h) do { _Pragma("unroll") for (int m = 0; m < 4; ++m) _Pragma("unroll") for (int k = 0; k < 2; ++k) dst[m][k] = *(const PG8_LAS bf16x8*)(lds + PG8_SA(b, h) + aoff + m * 2048 + k * 1024); } while (0)
; #define PG8_LDB(dst, b, h) do { _Pragma("unroll") for (int n = 0; n < 2; ++n) _Pragma("unroll") for (int k = 0; k < 2; ++k) dst[n][k] = *(const PG8_LAS bf16x8*)(lds + PG8_SB(b, h) + boff + n * 2048 + k * 1024); } while (0)
; #define PG8_WAIT_V(n) asm volatile("s_waitcnt vmcnt(" #n ")" ::: "memory")
; #define PG8_WAIT_L(n) asm volatile("s_waitcnt lgkmcnt(" #n ")" ::: "memory")
; #define PG8_BAR __builtin_amdgcn_s_barrier()
; #define PG8_SCHED __builtin_amdgcn_sched_barrier(0)
; template <class Epi, class Sched, bool ALIGN_EPI = false, bool SP2 = false>
; __device__ __forceinline__ void gemm_phase(PG8_LAS unsigned char* lds, const Gemm g, const Sched& S, const Epi& E) {
;     ...
;         const bool has_next = S.next(ui + 1, nxt);
;         const char* nA = has_next ? (const char*)g.A + (size_t)nxt.pm * tstep : cA; const char* nB = has_next ? (const char*)g.Bt + (size_t)nxt.pn * tstep : cB;
;         for (int t = 0; t < nt; t += 2) {
;             const bool last = (t == nt - 2);
;             const char* a1 = cA + (size_t)(t + 1) * kstep;
;             const char* a2 = last ? nA : cA + (size_t)(t + 2) * kstep; const char* b2 = last ? nB : cB + (size_t)(t + 2) * kstep;
;             const char* a3 = a2 + kstep; const char* b3 = b2 + kstep;
;             if (last && has_next) S.a_ready(nxt);
;             if constexpr (SP2) {
;             PG8_LDB(B0, 0, 0); PG8_LDB(B1, 0, 1); PG8_SCHED; PG8_LDA(At, 0, 0); PG8_STAGE(PG8_SA(1, 1), a1 + hstep, voffA);
;             PG8_WAIT_V(8); PG8_WAIT_L(0); PG8_BAR; PG8_MMA(0, 0, At, B0); PG8_MMA(0, 1, At, B1); PG8_BAR; PG8_SCHED;
;     ...
; #pragma unroll
;         for (int a = 0; a < 2; ++a)
; #pragma unroll
;             for (int b = 0; b < 2; ++b)
; #pragma unroll
;                 for (int m = 0; m < 4; ++m)
; #pragma unroll
;                     for (int n = 0; n < 2; ++n) acc[a][b][m][n] = (f32x4){0.f, 0.f, 0.f, 0.f};
.Lstg_done:
	s_cmp_lg_u32 s65, 1
	s_cselect_b32 s100, 1, 0
	s_ashr_i32 s27, s26, 31
	s_lshl_b64 s[12:13], s[26:27], 20
	s_add_u32 s94, s18, s12
	s_addc_u32 s95, s19, s13
	s_and_b64 s[12:13], s[46:47], exec
	s_cselect_b32 s27, s95, s69
	s_cselect_b32 s86, s94, s68
	s_ashr_i32 s17, s16, 31
	s_lshl_b64 s[12:13], s[16:17], 20
	v_readlane_b32 s14, v254, 38
	v_readlane_b32 s15, v254, 39
	s_add_u32 s14, s14, s12
	s_addc_u32 s15, s15, s13
	s_and_b64 s[12:13], s[46:47], exec
	s_cselect_b32 s17, s15, s11
	s_cselect_b32 s88, s14, s10
	s_add_u32 vcc_lo, s68, 0x80080
	s_addc_u32 vcc_hi, s69, 0
	s_add_u32 s21, s10, 0x100
	v_mov_b32_e32 v6, 0
	s_addc_u32 s12, s11, 0
	s_mov_b32 s13, -2
	v_mov_b32_e32 v7, v6
	v_mov_b32_e32 v8, v6
	v_mov_b32_e32 v9, v6
	v_mov_b32_e32 v70, v6
	v_mov_b32_e32 v71, v6
	v_mov_b32_e32 v72, v6
	v_mov_b32_e32 v73, v6
	v_mov_b32_e32 v14, v6
	v_mov_b32_e32 v15, v6
	v_mov_b32_e32 v16, v6
	v_mov_b32_e32 v17, v6
	v_mov_b32_e32 v78, v6
	v_mov_b32_e32 v79, v6
	v_mov_b32_e32 v80, v6
	v_mov_b32_e32 v81, v6
	v_mov_b32_e32 v22, v6
	v_mov_b32_e32 v23, v6
	v_mov_b32_e32 v24, v6
	v_mov_b32_e32 v25, v6
	v_mov_b32_e32 v86, v6
	v_mov_b32_e32 v87, v6
	v_mov_b32_e32 v88, v6
	v_mov_b32_e32 v89, v6
	v_mov_b32_e32 v26, v6
	v_mov_b32_e32 v27, v6
	v_mov_b32_e32 v28, v6
	v_mov_b32_e32 v29, v6
	v_mov_b32_e32 v90, v6
	v_mov_b32_e32 v91, v6
	v_mov_b32_e32 v92, v6
	v_mov_b32_e32 v93, v6
	v_mov_b32_e32 v2, v6
	v_mov_b32_e32 v3, v6
	v_mov_b32_e32 v4, v6
	v_mov_b32_e32 v5, v6
	v_mov_b32_e32 v66, v6
	v_mov_b32_e32 v67, v6
	v_mov_b32_e32 v68, v6
	v_mov_b32_e32 v69, v6
	v_mov_b32_e32 v10, v6
	v_mov_b32_e32 v11, v6
	v_mov_b32_e32 v12, v6
	v_mov_b32_e32 v13, v6
	v_mov_b32_e32 v74, v6
	v_mov_b32_e32 v75, v6
	v_mov_b32_e32 v76, v6
	v_mov_b32_e32 v77, v6
	v_mov_b32_e32 v18, v6
	v_mov_b32_e32 v19, v6
	v_mov_b32_e32 v20, v6
	v_mov_b32_e32 v21, v6
	v_mov_b32_e32 v82, v6
	v_mov_b32_e32 v83, v6
	v_mov_b32_e32 v84, v6
	v_mov_b32_e32 v85, v6
	v_mov_b32_e32 v30, v6
	v_mov_b32_e32 v31, v6
	v_mov_b32_e32 v32, v6
	v_mov_b32_e32 v33, v6
	v_mov_b32_e32 v94, v6
	v_mov_b32_e32 v95, v6
	v_mov_b32_e32 v96, v6
	v_mov_b32_e32 v97, v6
	v_mov_b32_e32 v38, v6
	v_mov_b32_e32 v39, v6
	v_mov_b32_e32 v40, v6
	v_mov_b32_e32 v41, v6
	v_mov_b32_e32 v102, v6
	v_mov_b32_e32 v103, v6
	v_mov_b32_e32 v104, v6
	v_mov_b32_e32 v105, v6
	v_mov_b32_e32 v46, v6
	v_mov_b32_e32 v47, v6
	v_mov_b32_e32 v48, v6
	v_mov_b32_e32 v49, v6
	v_mov_b32_e32 v110, v6
	v_mov_b32_e32 v111, v6
	v_mov_b32_e32 v112, v6
	v_mov_b32_e32 v113, v6
	v_mov_b32_e32 v54, v6
	v_mov_b32_e32 v55, v6
	v_mov_b32_e32 v56, v6
	v_mov_b32_e32 v57, v6
	v_mov_b32_e32 v126, v6
	v_mov_b32_e32 v127, v6
	v_mov_b32_e32 v128, v6
	v_mov_b32_e32 v129, v6
	v_mov_b32_e32 v58, v6
	v_mov_b32_e32 v59, v6
	v_mov_b32_e32 v60, v6
	v_mov_b32_e32 v61, v6
	v_mov_b32_e32 v134, v6
	v_mov_b32_e32 v135, v6
	v_mov_b32_e32 v136, v6
	v_mov_b32_e32 v137, v6
	v_mov_b32_e32 v34, v6
	v_mov_b32_e32 v35, v6
	v_mov_b32_e32 v36, v6
	v_mov_b32_e32 v37, v6
	v_mov_b32_e32 v98, v6
	v_mov_b32_e32 v99, v6
	v_mov_b32_e32 v100, v6
	v_mov_b32_e32 v101, v6
	v_mov_b32_e32 v42, v6
	v_mov_b32_e32 v43, v6
	v_mov_b32_e32 v44, v6
	v_mov_b32_e32 v45, v6
	v_mov_b32_e32 v106, v6
	v_mov_b32_e32 v107, v6
	v_mov_b32_e32 v108, v6
	v_mov_b32_e32 v109, v6
	v_mov_b32_e32 v50, v6
	v_mov_b32_e32 v51, v6
	v_mov_b32_e32 v52, v6
	v_mov_b32_e32 v53, v6
	v_mov_b32_e32 v122, v6
	v_mov_b32_e32 v123, v6
	v_mov_b32_e32 v124, v6
	v_mov_b32_e32 v125, v6
	v_mov_b32_e32 v62, v6
	v_mov_b32_e32 v63, v6
	v_mov_b32_e32 v64, v6
	v_mov_b32_e32 v65, v6
	v_mov_b32_e32 v142, v6
	v_mov_b32_e32 v143, v6
	v_mov_b32_e32 v144, v6
	v_mov_b32_e32 v145, v6
.LBB0_38:
	s_add_u32 s10, vcc_lo, 0xfff80080
	s_addc_u32 s11, vcc_hi, -1
	s_add_i32 s84, 0, 0x10000
	s_cmp_eq_u32 s13, 28
	s_cselect_b32 s69, s27, s11
	s_cselect_b32 s68, s86, s10
	s_cselect_b32 s11, s17, s12
	s_cselect_b32 s10, s88, s21
	s_add_i32 s93, 0, 0x14000
	v_add_u32_e32 v138, s84, v194
	v_add_u32_e32 v164, s93, v194
	ds_read_b128 v[114:117], v138
	ds_read_b128 v[118:121], v138 offset:1024
	ds_read_b128 v[130:133], v138 offset:2048
	ds_read_b128 v[138:141], v138 offset:3072
	ds_read_b128 v[146:149], v164
	ds_read_b128 v[156:159], v164 offset:1024
	ds_read_b128 v[160:163], v164 offset:2048
	ds_read_b128 v[164:167], v164 offset:3072
	v_lshl_add_u64 v[208:209], vcc, 0, v[152:153]
	s_add_i32 m0, s2, 0xc000
	ds_read_b128 v[168:171], v199
	ds_read_b128 v[172:175], v199 offset:1024
	ds_read_b128 v[176:179], v199 offset:2048
	ds_read_b128 v[180:183], v199 offset:3072
	ds_read_b128 v[184:187], v199 offset:4096
	ds_read_b128 v[188:191], v199 offset:5120
	ds_read_b128 v[200:203], v199 offset:6144
	ds_read_b128 v[204:207], v199 offset:7168
	global_load_lds_dwordx4 v[208:209], off
	v_lshl_add_u64 v[208:209], vcc, 0, v[154:155]
	s_add_i32 m0, s2, 0xe000
	s_nop 0
	global_load_lds_dwordx4 v[208:209], off
	s_cmp_eq_u32 s100, 1
	s_cbranch_scc1 .Lkd2_up_0
	s_waitcnt vmcnt(8)
; #define PG8_STAGE(bufoff, gbase, voff) do { _Pragma("unroll") for (int _i = 0; _i < 2; ++_i) \
;         __builtin_amdgcn_global_load_lds((const unsigned*)((const char*)(gbase) + (voff)[_i]), (PG8_LAS unsigned*)(lds + (bufoff) + ldsw + _i * 8192), 16, 0, 0); } while (0)
; #define PG8_LDA(dst, b, h) do { _Pragma("unroll") for (int m = 0; m < 4; ++m) _Pragma("unroll") for (int k = 0; k < 2; ++k) dst[m][k] = *(const PG8_LAS bf16x8*)(lds + PG8_SA(b, h) + aoff + m * 2048 + k * 1024); } while (0)
; #define PG8_LDB(dst, b, h) do { _Pragma("unroll") for (int n = 0; n < 2; ++n) _Pragma("unroll") for (int k = 0; k < 2; ++k) dst[n][k] = *(const PG8_LAS bf16x8*)(lds + PG8_SB(b, h) + boff + n * 2048 + k * 1024); } while (0)
; #define PG8_MMA(ai, bj, At, Bt) do { __builtin_amdgcn_s_setprio(1); _Pragma("unroll") for (int m = 0; m < 4; ++m) _Pragma("unroll") for (int n = 0; n < 2; ++n) _Pragma("unroll") for (int k = 0; k < 2; ++k) \
;         acc[ai][bj][m][n] = __builtin_amdgcn_mfma_f32_16x16x32_bf16(Bt[n][k], At[m][k], acc[ai][bj][m][n], 0, 0, 0); __builtin_amdgcn_s_setprio(0); } while (0)
; #define PG8_WAIT_V(n) asm volatile("s_waitcnt vmcnt(" #n ")" ::: "memory")
; #define PG8_WAIT_L(n) asm volatile("s_waitcnt lgkmcnt(" #n ")" ::: "memory")
; #define PG8_BAR __builtin_amdgcn_s_barrier()
; #define PG8_SCHED __builtin_amdgcn_sched_barrier(0)
; template <class Epi, class Sched, bool ALIGN_EPI = false, bool SP2 = false>
; __device__ __forceinline__ void gemm_phase(PG8_LAS unsigned char* lds, const Gemm g, const Sched& S, const Epi& E) {
;     ...
;             PG8_LDB(B0, 0, 0); PG8_LDB(B1, 0, 1); PG8_SCHED; PG8_LDA(At, 0, 0); PG8_STAGE(PG8_SA(1, 1), a1 + hstep, voffA);
;             PG8_WAIT_V(8); PG8_WAIT_L(0); PG8_BAR; PG8_MMA(0, 0, At, B0); PG8_MMA(0, 1, At, B1); PG8_BAR; PG8_SCHED;
;             PG8_LDA(At, 0, 1); PG8_STAGE(PG8_SB(0, 0), b2, voffB); PG8_STAGE(PG8_SB(0, 1), b2 + hstep, voffB); PG8_STAGE(PG8_SA(0, 0), a2, voffA);
;             PG8_WAIT_V(8); PG8_WAIT_L(0); PG8_BAR; PG8_MMA(1, 0, At, B0); PG8_MMA(1, 1, At, B1); PG8_BAR; PG8_SCHED;
.Lkd2_up_0:
	s_waitcnt lgkmcnt(0)
	s_barrier
	s_setprio 1
	s_waitcnt lgkmcnt(0)
	v_mfma_f32_16x16x32_bf16 v[142:145], v[114:117], v[168:171], v[142:145]
	v_mfma_f32_16x16x32_bf16 v[62:65], v[130:133], v[168:171], v[62:65]
	v_mfma_f32_16x16x32_bf16 v[122:125], v[114:117], v[176:179], v[122:125]
	v_mfma_f32_16x16x32_bf16 v[50:53], v[130:133], v[176:179], v[50:53]
	v_mfma_f32_16x16x32_bf16 v[106:109], v[114:117], v[184:187], v[106:109]
	v_mfma_f32_16x16x32_bf16 v[42:45], v[130:133], v[184:187], v[42:45]
	v_mfma_f32_16x16x32_bf16 v[98:101], v[114:117], v[200:203], v[98:101]
	v_mfma_f32_16x16x32_bf16 v[34:37], v[130:133], v[200:203], v[34:37]
	v_mfma_f32_16x16x32_bf16 v[142:145], v[118:121], v[172:175], v[142:145]
	v_mfma_f32_16x16x32_bf16 v[62:65], v[138:141], v[172:175], v[62:65]
	v_mfma_f32_16x16x32_bf16 v[122:125], v[118:121], v[180:183], v[122:125]
	v_mfma_f32_16x16x32_bf16 v[50:53], v[138:141], v[180:183], v[50:53]
	v_mfma_f32_16x16x32_bf16 v[106:109], v[118:121], v[188:191], v[106:109]
	v_mfma_f32_16x16x32_bf16 v[42:45], v[138:141], v[188:191], v[42:45]
	v_mfma_f32_16x16x32_bf16 v[98:101], v[118:121], v[204:207], v[98:101]
	v_mfma_f32_16x16x32_bf16 v[34:37], v[138:141], v[204:207], v[34:37]
	s_setprio 0
	s_setprio 1
	v_mfma_f32_16x16x32_bf16 v[134:137], v[146:149], v[168:171], v[134:137]
	v_mfma_f32_16x16x32_bf16 v[58:61], v[160:163], v[168:171], v[58:61]
	v_mfma_f32_16x16x32_bf16 v[126:129], v[146:149], v[176:179], v[126:129]
	v_mfma_f32_16x16x32_bf16 v[54:57], v[160:163], v[176:179], v[54:57]
	v_mfma_f32_16x16x32_bf16 v[110:113], v[146:149], v[184:187], v[110:113]
	v_mfma_f32_16x16x32_bf16 v[46:49], v[160:163], v[184:187], v[46:49]
	v_mfma_f32_16x16x32_bf16 v[102:105], v[146:149], v[200:203], v[102:105]
	v_mfma_f32_16x16x32_bf16 v[38:41], v[160:163], v[200:203], v[38:41]
	v_mfma_f32_16x16x32_bf16 v[134:137], v[156:159], v[172:175], v[134:137]
	v_mfma_f32_16x16x32_bf16 v[58:61], v[164:167], v[172:175], v[58:61]
	v_mfma_f32_16x16x32_bf16 v[126:129], v[156:159], v[180:183], v[126:129]
	v_mfma_f32_16x16x32_bf16 v[54:57], v[164:167], v[180:183], v[54:57]
	v_mfma_f32_16x16x32_bf16 v[110:113], v[156:159], v[188:191], v[110:113]
	v_mfma_f32_16x16x32_bf16 v[46:49], v[164:167], v[188:191], v[46:49]
	v_mfma_f32_16x16x32_bf16 v[102:105], v[156:159], v[204:207], v[102:105]
	v_mfma_f32_16x16x32_bf16 v[38:41], v[164:167], v[204:207], v[38:41]
	s_setprio 0
	s_barrier
	s_add_i32 s84, s84, s1
	v_lshl_add_u64 v[208:209], s[10:11], 0, v[0:1]
	s_mov_b32 m0, s84
	ds_read_b128 v[168:171], v199 offset:16384
	ds_read_b128 v[172:175], v199 offset:17408
	ds_read_b128 v[176:179], v199 offset:18432
	ds_read_b128 v[180:183], v199 offset:19456
	ds_read_b128 v[184:187], v199 offset:20480
	ds_read_b128 v[188:191], v199 offset:21504
	ds_read_b128 v[200:203], v199 offset:22528
	ds_read_b128 v[204:207], v199 offset:23552
	global_load_lds_dwordx4 v[208:209], off
	s_add_i32 m0, s84, 0x2000
	s_add_u32 s84, s10, 0x80000
	v_lshl_add_u64 v[210:211], s[10:11], 0, v[150:151]
	s_addc_u32 s85, s11, 0
	s_add_i32 s93, s93, s1
	global_load_lds_dwordx4 v[210:211], off
	v_lshl_add_u64 v[212:213], s[84:85], 0, v[0:1]
	s_mov_b32 m0, s93
	v_lshl_add_u64 v[214:215], s[68:69], 0, v[150:151]
	global_load_lds_dwordx4 v[212:213], off
	v_lshl_add_u64 v[212:213], s[84:85], 0, v[150:151]
	s_add_i32 m0, s93, 0x2000
	s_nop 0
	global_load_lds_dwordx4 v[212:213], off
	v_lshl_add_u64 v[212:213], s[68:69], 0, v[0:1]
	s_mov_b32 m0, s2
	s_nop 0
	global_load_lds_dwordx4 v[212:213], off
	s_mov_b32 m0, s4
	s_nop 0
	global_load_lds_dwordx4 v[214:215], off
	s_cmp_eq_u32 s100, 1
	s_cbranch_scc1 .Lkd2_up_1
	s_waitcnt vmcnt(8)
.Lkd2_up_1:
	s_waitcnt lgkmcnt(0)
	s_barrier
	s_setprio 1
	s_waitcnt lgkmcnt(0)
	v_mfma_f32_16x16x32_bf16 v[94:97], v[114:117], v[168:171], v[94:97]
	v_mfma_f32_16x16x32_bf16 v[30:33], v[130:133], v[168:171], v[30:33]
	v_mfma_f32_16x16x32_bf16 v[82:85], v[114:117], v[176:179], v[82:85]
	v_mfma_f32_16x16x32_bf16 v[18:21], v[130:133], v[176:179], v[18:21]
	v_mfma_f32_16x16x32_bf16 v[74:77], v[114:117], v[184:187], v[74:77]
	v_mfma_f32_16x16x32_bf16 v[10:13], v[130:133], v[184:187], v[10:13]
	v_mfma_f32_16x16x32_bf16 v[66:69], v[114:117], v[200:203], v[66:69]
	v_mfma_f32_16x16x32_bf16 v[2:5], v[130:133], v[200:203], v[2:5]
	v_mfma_f32_16x16x32_bf16 v[94:97], v[118:121], v[172:175], v[94:97]
	v_mfma_f32_16x16x32_bf16 v[30:33], v[138:141], v[172:175], v[30:33]
	v_mfma_f32_16x16x32_bf16 v[82:85], v[118:121], v[180:183], v[82:85]
	v_mfma_f32_16x16x32_bf16 v[18:21], v[138:141], v[180:183], v[18:21]
	v_mfma_f32_16x16x32_bf16 v[74:77], v[118:121], v[188:191], v[74:77]
	v_mfma_f32_16x16x32_bf16 v[10:13], v[138:141], v[188:191], v[10:13]
	v_mfma_f32_16x16x32_bf16 v[66:69], v[118:121], v[204:207], v[66:69]
	v_mfma_f32_16x16x32_bf16 v[2:5], v[138:141], v[204:207], v[2:5]
	s_setprio 0
	s_setprio 1
	v_mfma_f32_16x16x32_bf16 v[90:93], v[146:149], v[168:171], v[90:93]
	v_mfma_f32_16x16x32_bf16 v[26:29], v[160:163], v[168:171], v[26:29]
	v_mfma_f32_16x16x32_bf16 v[86:89], v[146:149], v[176:179], v[86:89]
	v_mfma_f32_16x16x32_bf16 v[22:25], v[160:163], v[176:179], v[22:25]
	v_mfma_f32_16x16x32_bf16 v[78:81], v[146:149], v[184:187], v[78:81]
	v_mfma_f32_16x16x32_bf16 v[14:17], v[160:163], v[184:187], v[14:17]
	v_mfma_f32_16x16x32_bf16 v[70:73], v[146:149], v[200:203], v[70:73]
	v_mfma_f32_16x16x32_bf16 v[6:9], v[160:163], v[200:203], v[6:9]
	v_mfma_f32_16x16x32_bf16 v[90:93], v[156:159], v[172:175], v[90:93]
	v_mfma_f32_16x16x32_bf16 v[26:29], v[164:167], v[172:175], v[26:29]
	v_mfma_f32_16x16x32_bf16 v[86:89], v[156:159], v[180:183], v[86:89]
	v_mfma_f32_16x16x32_bf16 v[22:25], v[164:167], v[180:183], v[22:25]
	v_mfma_f32_16x16x32_bf16 v[78:81], v[156:159], v[188:191], v[78:81]
	v_mfma_f32_16x16x32_bf16 v[14:17], v[164:167], v[188:191], v[14:17]
	v_mfma_f32_16x16x32_bf16 v[70:73], v[156:159], v[204:207], v[70:73]
	v_mfma_f32_16x16x32_bf16 v[6:9], v[164:167], v[204:207], v[6:9]
	s_setprio 0
	s_barrier
; #define PG8_STAGE(bufoff, gbase, voff) do { _Pragma("unroll") for (int _i = 0; _i < 2; ++_i) \
;         __builtin_amdgcn_global_load_lds((const unsigned*)((const char*)(gbase) + (voff)[_i]), (PG8_LAS unsigned*)(lds + (bufoff) + ldsw + _i * 8192), 16, 0, 0); } while (0)
; #define PG8_LDA(dst, b, h) do { _Pragma("unroll") for (int m = 0; m < 4; ++m) _Pragma("unroll") for (int k = 0; k < 2; ++k) dst[m][k] = *(const PG8_LAS bf16x8*)(lds + PG8_SA(b, h) + aoff + m * 2048 + k * 1024); } while (0)
; #define PG8_LDB(dst, b, h) do { _Pragma("unroll") for (int n = 0; n < 2; ++n) _Pragma("unroll") for (int k = 0; k < 2; ++k) dst[n][k] = *(const PG8_LAS bf16x8*)(lds + PG8_SB(b, h) + boff + n * 2048 + k * 1024); } while (0)
; #define PG8_MMA(ai, bj, At, Bt) do { __builtin_amdgcn_s_setprio(1); _Pragma("unroll") for (int m = 0; m < 4; ++m) _Pragma("unroll") for (int n = 0; n < 2; ++n) _Pragma("unroll") for (int k = 0; k < 2; ++k) \
;         acc[ai][bj][m][n] = __builtin_amdgcn_mfma_f32_16x16x32_bf16(Bt[n][k], At[m][k], acc[ai][bj][m][n], 0, 0, 0); __builtin_amdgcn_s_setprio(0); } while (0)
; #define PG8_WAIT_V(n) asm volatile("s_waitcnt vmcnt(" #n ")" ::: "memory")
; #define PG8_WAIT_L(n) asm volatile("s_waitcnt lgkmcnt(" #n ")" ::: "memory")
; #define PG8_BAR __builtin_amdgcn_s_barrier()
; #define PG8_SCHED __builtin_amdgcn_sched_barrier(0)
; template <class Epi, class Sched, bool ALIGN_EPI = false, bool SP2 = false>
; __device__ __forceinline__ void gemm_phase(PG8_LAS unsigned char* lds, const Gemm g, const Sched& S, const Epi& E) {
;     ...
;             PG8_LDB(B0, 1, 0); PG8_LDB(B1, 1, 1); PG8_SCHED; PG8_LDA(At, 1, 0); PG8_STAGE(PG8_SA(0, 1), a2 + hstep, voffA);
;             PG8_WAIT_V(8); PG8_WAIT_L(0); PG8_BAR; PG8_MMA(0, 0, At, B0); PG8_MMA(0, 1, At, B1); PG8_BAR; PG8_SCHED;
;             PG8_LDA(At, 1, 1); PG8_STAGE(PG8_SB(1, 0), b3, voffB); PG8_STAGE(PG8_SB(1, 1), b3 + hstep, voffB); PG8_STAGE(PG8_SA(1, 0), a3, voffA);
;             PG8_WAIT_V(8); PG8_WAIT_L(0); PG8_BAR; PG8_MMA(1, 0, At, B0); PG8_MMA(1, 1, At, B1); PG8_BAR; PG8_SCHED;
	s_add_i32 s84, 0, 0x18000
	s_add_i32 s85, 0, 0x1c000
	v_add_u32_e32 v138, s84, v194
	v_add_u32_e32 v164, s85, v194
	ds_read_b128 v[114:117], v138
	ds_read_b128 v[118:121], v138 offset:1024
	ds_read_b128 v[130:133], v138 offset:2048
	ds_read_b128 v[138:141], v138 offset:3072
	ds_read_b128 v[146:149], v164
	ds_read_b128 v[156:159], v164 offset:1024
	ds_read_b128 v[160:163], v164 offset:2048
	ds_read_b128 v[164:167], v164 offset:3072
	s_add_u32 s68, s68, 0x80000
	s_addc_u32 s69, s69, 0
	s_mov_b32 m0, s5
	v_lshl_add_u64 v[216:217], s[68:69], 0, v[0:1]
	ds_read_b128 v[168:171], v199 offset:32768
	ds_read_b128 v[172:175], v199 offset:33792
	ds_read_b128 v[176:179], v199 offset:34816
	ds_read_b128 v[180:183], v199 offset:35840
	ds_read_b128 v[184:187], v199 offset:36864
	ds_read_b128 v[188:191], v199 offset:37888
	ds_read_b128 v[200:203], v199 offset:38912
	ds_read_b128 v[204:207], v199 offset:39936
	global_load_lds_dwordx4 v[216:217], off
	v_lshl_add_u64 v[216:217], s[68:69], 0, v[150:151]
	s_mov_b32 m0, s6
	s_nop 0
	global_load_lds_dwordx4 v[216:217], off
	s_cmp_eq_u32 s100, 1
	s_cbranch_scc1 .Lkd2_up_2
	s_waitcnt vmcnt(8)
.Lkd2_up_2:
	s_mov_b32 s100, 0
	s_waitcnt lgkmcnt(0)
	s_barrier
	s_setprio 1
	s_waitcnt lgkmcnt(0)
	v_mfma_f32_16x16x32_bf16 v[142:145], v[114:117], v[168:171], v[142:145]
	v_mfma_f32_16x16x32_bf16 v[62:65], v[130:133], v[168:171], v[62:65]
	v_mfma_f32_16x16x32_bf16 v[122:125], v[114:117], v[176:179], v[122:125]
	v_mfma_f32_16x16x32_bf16 v[50:53], v[130:133], v[176:179], v[50:53]
	v_mfma_f32_16x16x32_bf16 v[106:109], v[114:117], v[184:187], v[106:109]
	v_mfma_f32_16x16x32_bf16 v[42:45], v[130:133], v[184:187], v[42:45]
	v_mfma_f32_16x16x32_bf16 v[98:101], v[114:117], v[200:203], v[98:101]
	v_mfma_f32_16x16x32_bf16 v[34:37], v[130:133], v[200:203], v[34:37]
	v_mfma_f32_16x16x32_bf16 v[142:145], v[118:121], v[172:175], v[142:145]
	v_mfma_f32_16x16x32_bf16 v[62:65], v[138:141], v[172:175], v[62:65]
	v_mfma_f32_16x16x32_bf16 v[122:125], v[118:121], v[180:183], v[122:125]
	v_mfma_f32_16x16x32_bf16 v[50:53], v[138:141], v[180:183], v[50:53]
	v_mfma_f32_16x16x32_bf16 v[106:109], v[118:121], v[188:191], v[106:109]
	v_mfma_f32_16x16x32_bf16 v[42:45], v[138:141], v[188:191], v[42:45]
	v_mfma_f32_16x16x32_bf16 v[98:101], v[118:121], v[204:207], v[98:101]
	v_mfma_f32_16x16x32_bf16 v[34:37], v[138:141], v[204:207], v[34:37]
	s_setprio 0
	s_setprio 1
	v_mfma_f32_16x16x32_bf16 v[134:137], v[146:149], v[168:171], v[134:137]
	v_mfma_f32_16x16x32_bf16 v[58:61], v[160:163], v[168:171], v[58:61]
	v_mfma_f32_16x16x32_bf16 v[126:129], v[146:149], v[176:179], v[126:129]
	v_mfma_f32_16x16x32_bf16 v[54:57], v[160:163], v[176:179], v[54:57]
	v_mfma_f32_16x16x32_bf16 v[110:113], v[146:149], v[184:187], v[110:113]
	v_mfma_f32_16x16x32_bf16 v[46:49], v[160:163], v[184:187], v[46:49]
	v_mfma_f32_16x16x32_bf16 v[102:105], v[146:149], v[200:203], v[102:105]
	v_mfma_f32_16x16x32_bf16 v[38:41], v[160:163], v[200:203], v[38:41]
	v_mfma_f32_16x16x32_bf16 v[134:137], v[156:159], v[172:175], v[134:137]
	v_mfma_f32_16x16x32_bf16 v[58:61], v[164:167], v[172:175], v[58:61]
	v_mfma_f32_16x16x32_bf16 v[126:129], v[156:159], v[180:183], v[126:129]
	v_mfma_f32_16x16x32_bf16 v[54:57], v[164:167], v[180:183], v[54:57]
	v_mfma_f32_16x16x32_bf16 v[110:113], v[156:159], v[188:191], v[110:113]
	v_mfma_f32_16x16x32_bf16 v[46:49], v[164:167], v[188:191], v[46:49]
	v_mfma_f32_16x16x32_bf16 v[102:105], v[156:159], v[204:207], v[102:105]
	v_mfma_f32_16x16x32_bf16 v[38:41], v[164:167], v[204:207], v[38:41]
	s_setprio 0
	s_barrier
	s_add_i32 s68, s84, s1
	v_lshl_add_u64 v[208:209], v[208:209], 0, s[34:35]
	s_mov_b32 m0, s68
	ds_read_b128 v[168:171], v199 offset:49152
	ds_read_b128 v[172:175], v199 offset:50176
	ds_read_b128 v[176:179], v199 offset:51200
	ds_read_b128 v[180:183], v199 offset:52224
	ds_read_b128 v[184:187], v199 offset:53248
	ds_read_b128 v[188:191], v199 offset:54272
	ds_read_b128 v[200:203], v199 offset:55296
	ds_read_b128 v[204:207], v199 offset:56320
	global_load_lds_dwordx4 v[208:209], off
	s_add_i32 m0, s68, 0x2000
	s_add_u32 s10, s10, 0x80080
	v_lshl_add_u64 v[208:209], v[210:211], 0, s[34:35]
	s_addc_u32 s11, s11, 0
	s_add_i32 s68, s85, s1
	global_load_lds_dwordx4 v[208:209], off
	v_lshl_add_u64 v[208:209], s[10:11], 0, v[0:1]
	s_mov_b32 m0, s68
	s_nop 0
	global_load_lds_dwordx4 v[208:209], off
	v_lshl_add_u64 v[208:209], s[10:11], 0, v[150:151]
	s_add_i32 m0, s68, 0x2000
	s_nop 0
	global_load_lds_dwordx4 v[208:209], off
	v_lshl_add_u64 v[208:209], v[212:213], 0, s[34:35]
	s_mov_b32 m0, s7
	s_nop 0
	global_load_lds_dwordx4 v[208:209], off
	v_lshl_add_u64 v[208:209], v[214:215], 0, s[34:35]
	s_mov_b32 m0, s30
	s_nop 0
	global_load_lds_dwordx4 v[208:209], off
	s_waitcnt vmcnt(8)
	s_waitcnt lgkmcnt(0)
	s_barrier
; #define PG8_STAGE(bufoff, gbase, voff) do { _Pragma("unroll") for (int _i = 0; _i < 2; ++_i) \
;         __builtin_amdgcn_global_load_lds((const unsigned*)((const char*)(gbase) + (voff)[_i]), (PG8_LAS unsigned*)(lds + (bufoff) + ldsw + _i * 8192), 16, 0, 0); } while (0)
; #define PG8_LDA(dst, b, h) do { _Pragma("unroll") for (int m = 0; m < 4; ++m) _Pragma("unroll") for (int k = 0; k < 2; ++k) dst[m][k] = *(const PG8_LAS bf16x8*)(lds + PG8_SA(b, h) + aoff + m * 2048 + k * 1024); } while (0)
; #define PG8_MMA(ai, bj, At, Bt) do { __builtin_amdgcn_s_setprio(1); _Pragma("unroll") for (int m = 0; m < 4; ++m) _Pragma("unroll") for (int n = 0; n < 2; ++n) _Pragma("unroll") for (int k = 0; k < 2; ++k) \
;         acc[ai][bj][m][n] = __builtin_amdgcn_mfma_f32_16x16x32_bf16(Bt[n][k], At[m][k], acc[ai][bj][m][n], 0, 0, 0); __builtin_amdgcn_s_setprio(0); } while (0)
; #define PG8_WAIT_V(n) asm volatile("s_waitcnt vmcnt(" #n ")" ::: "memory")
; #define PG8_WAIT_L(n) asm volatile("s_waitcnt lgkmcnt(" #n ")" ::: "memory")
; #define PG8_BAR __builtin_amdgcn_s_barrier()
; #define PG8_SCHED __builtin_amdgcn_sched_barrier(0)
; template <class Epi, class Sched, bool ALIGN_EPI = false, bool SP2 = false>
; __device__ __forceinline__ void gemm_phase(PG8_LAS unsigned char* lds, const Gemm g, const Sched& S, const Epi& E) {
;     ...
;         for (int t = 0; t < nt; t += 2) {
;             const bool last = (t == nt - 2);
;     ...
;             PG8_WAIT_V(8); PG8_WAIT_L(0); PG8_BAR; PG8_MMA(0, 0, At, B0); PG8_MMA(0, 1, At, B1); PG8_BAR; PG8_SCHED;
;             PG8_LDA(At, 1, 1); PG8_STAGE(PG8_SB(1, 0), b3, voffB); PG8_STAGE(PG8_SB(1, 1), b3 + hstep, voffB); PG8_STAGE(PG8_SA(1, 0), a3, voffA);
;             PG8_WAIT_V(8); PG8_WAIT_L(0); PG8_BAR; PG8_MMA(1, 0, At, B0); PG8_MMA(1, 1, At, B1); PG8_BAR; PG8_SCHED;
;     ...
;         if constexpr (ALIGN_EPI) { if (wr == 0) PG8_BAR; }
	s_setprio 1
	s_waitcnt lgkmcnt(0)
	v_mfma_f32_16x16x32_bf16 v[94:97], v[114:117], v[168:171], v[94:97]
	v_mfma_f32_16x16x32_bf16 v[30:33], v[130:133], v[168:171], v[30:33]
	v_mfma_f32_16x16x32_bf16 v[82:85], v[114:117], v[176:179], v[82:85]
	v_mfma_f32_16x16x32_bf16 v[18:21], v[130:133], v[176:179], v[18:21]
	v_mfma_f32_16x16x32_bf16 v[74:77], v[114:117], v[184:187], v[74:77]
	v_mfma_f32_16x16x32_bf16 v[10:13], v[130:133], v[184:187], v[10:13]
	v_mfma_f32_16x16x32_bf16 v[66:69], v[114:117], v[200:203], v[66:69]
	v_mfma_f32_16x16x32_bf16 v[2:5], v[130:133], v[200:203], v[2:5]
	v_mfma_f32_16x16x32_bf16 v[94:97], v[118:121], v[172:175], v[94:97]
	v_mfma_f32_16x16x32_bf16 v[30:33], v[138:141], v[172:175], v[30:33]
	v_mfma_f32_16x16x32_bf16 v[82:85], v[118:121], v[180:183], v[82:85]
	v_mfma_f32_16x16x32_bf16 v[18:21], v[138:141], v[180:183], v[18:21]
	v_mfma_f32_16x16x32_bf16 v[74:77], v[118:121], v[188:191], v[74:77]
	v_mfma_f32_16x16x32_bf16 v[10:13], v[138:141], v[188:191], v[10:13]
	v_mfma_f32_16x16x32_bf16 v[66:69], v[118:121], v[204:207], v[66:69]
	v_mfma_f32_16x16x32_bf16 v[2:5], v[138:141], v[204:207], v[2:5]
	s_setprio 0
	s_setprio 1
	v_mfma_f32_16x16x32_bf16 v[90:93], v[146:149], v[168:171], v[90:93]
	v_mfma_f32_16x16x32_bf16 v[26:29], v[160:163], v[168:171], v[26:29]
	v_mfma_f32_16x16x32_bf16 v[86:89], v[146:149], v[176:179], v[86:89]
	v_mfma_f32_16x16x32_bf16 v[22:25], v[160:163], v[176:179], v[22:25]
	v_mfma_f32_16x16x32_bf16 v[78:81], v[146:149], v[184:187], v[78:81]
	v_mfma_f32_16x16x32_bf16 v[14:17], v[160:163], v[184:187], v[14:17]
	v_mfma_f32_16x16x32_bf16 v[70:73], v[146:149], v[200:203], v[70:73]
	v_mfma_f32_16x16x32_bf16 v[6:9], v[160:163], v[200:203], v[6:9]
	v_mfma_f32_16x16x32_bf16 v[90:93], v[156:159], v[172:175], v[90:93]
	v_mfma_f32_16x16x32_bf16 v[26:29], v[164:167], v[172:175], v[26:29]
	v_mfma_f32_16x16x32_bf16 v[86:89], v[156:159], v[180:183], v[86:89]
	v_mfma_f32_16x16x32_bf16 v[22:25], v[164:167], v[180:183], v[22:25]
	v_mfma_f32_16x16x32_bf16 v[78:81], v[156:159], v[188:191], v[78:81]
	v_mfma_f32_16x16x32_bf16 v[14:17], v[164:167], v[188:191], v[14:17]
	v_mfma_f32_16x16x32_bf16 v[70:73], v[156:159], v[204:207], v[70:73]
	v_mfma_f32_16x16x32_bf16 v[6:9], v[164:167], v[204:207], v[6:9]
	s_setprio 0
	s_barrier
	s_add_i32 s13, s13, 2
	s_add_u32 vcc_lo, vcc_lo, 0x100
	s_addc_u32 vcc_hi, vcc_hi, 0
	s_add_u32 s21, s21, 0x100
	s_addc_u32 s12, s12, 0
	s_cmp_gt_u32 s13, 29
	s_cbranch_scc0 .LBB0_38
	s_and_b64 vcc, exec, s[58:59]
	s_cbranch_vccz .LBB0_41
	s_barrier
;     __device__ __forceinline__ void operator()(const f32x4 (&acc)[2][2][4][2], const Unit& u, int wr, int wc, int fr, int fq) const {
;     ...
;             for (int m = 0; m < 4; ++m) rs[ai][m] = __builtin_amdgcn_rsqf((float)ss[u.pm * BM + ai * HALF + wr * 64 + m * 16 + fr] * (1.f / (2048.f * 262144.f)) + 1e-6f);
; #pragma unroll
;         for (int n = 0; n < 2; ++n) {
;             const int cbase = 128 * u.pn + 32 * wc + 16 * n + 4 * fq;
;             const f32x4 w0 = *(const f32x4*)(cw + cbase), w1 = *(const f32x4*)(cw + FF + cbase), w2 = *(const f32x4*)(cw + 2 * FF + cbase), b4 = *(const f32x4*)(cb + cbase);
; template <class Epi, class Sched, bool ALIGN_EPI = false, bool SP2 = false>
; __device__ __forceinline__ void gemm_phase(PG8_LAS unsigned char* lds, const Gemm g, const Sched& S, const Epi& E) {
;     ...
;     for (;;) {
;         const bool has_next = S.next(ui + 1, nxt);
;         const char* nA = has_next ? (const char*)g.A + (size_t)nxt.pm * tstep : cA; const char* nB = has_next ? (const char*)g.Bt + (size_t)nxt.pn * tstep : cB;
;         for (int t = 0; t < nt; t += 2) {
;             const bool last = (t == nt - 2);
;             const char* a1 = cA + (size_t)(t + 1) * kstep;
;             const char* a2 = last ? nA : cA + (size_t)(t + 2) * kstep; const char* b2 = last ? nB : cB + (size_t)(t + 2) * kstep;
;             const char* a3 = a2 + kstep; const char* b3 = b2 + kstep;
;             if (last && has_next) S.a_ready(nxt);
.LBB0_41:
	s_add_u32 s98, s86, 0x80080
	s_addc_u32 s99, s27, 0
	v_lshl_add_u64 v[208:209], s[98:99], 0, v[152:153]
	s_add_i32 m0, s2, 0xc000
	s_nop 0
	global_load_lds_dwordx4 v[208:209], off
	v_lshl_add_u64 v[208:209], s[98:99], 0, v[154:155]
	s_add_i32 m0, s2, 0xe000
	s_nop 0
	global_load_lds_dwordx4 v[208:209], off
	s_waitcnt vmcnt(2)
	v_lshl_add_u32 v160, s66, 8, v193
	v_ashrrev_i32_e32 v161, 31, v160
	v_mov_b32_e32 v148, v227
	v_bfe_u32 v205, v227, 4, 1
	v_mul_u32_u24_e32 v205, 24, v205
	s_and_b32 s98, s65, 1
	s_lshl_b32 s98, s98, 12
	s_add_i32 s98, s98, 0x20000
	s_add_i32 s99, s98, 0x800
	v_lshl_add_u32 v114, v193, 3, s98
	ds_read_b64 v[146:147], v114
	v_lshl_or_b32 v156, s64, 7, v198
	v_ashrrev_i32_e32 v157, 31, v156
	ds_read_b64 v[190:191], v114 offset:128
	ds_read_b64 v[188:189], v114 offset:256
	ds_read_b64 v[186:187], v114 offset:384
	ds_read_b64 v[176:177], v114 offset:1024
	ds_read_b64 v[174:175], v114 offset:1152
	ds_read_b64 v[172:173], v114 offset:1280
	ds_read_b64 v[170:171], v114 offset:1408
	v_lshlrev_b64 v[158:159], 2, v[156:157]
	v_lshl_add_u32 v166, v198, 2, s99
	v_lshl_add_u64 v[118:119], s[60:61], 0, v[158:159]
	v_lshl_add_u64 v[120:121], s[62:63], 0, v[158:159]
	v_lshl_add_u64 v[164:165], s[54:55], 0, v[158:159]
	ds_read_b128 v[114:117], v166
	ds_read_b128 v[138:141], v166 offset:512
	ds_read_b128 v[130:133], v166 offset:1024
	s_nop 0
	ds_read_b128 v[118:121], v166 offset:1536
	s_waitcnt lgkmcnt(0)
	v_ffbh_u32_e32 v149, v147
	v_min_u32_e32 v149, 32, v149
	v_lshlrev_b64 v[146:147], v149, v[146:147]
	v_min_u32_e32 v146, 1, v146
	v_or_b32_e32 v146, v147, v146
	v_cvt_f32_u32_e32 v146, v146
	v_sub_u32_e32 v149, 32, v149
	v_and_b32_e32 v147, 48, v148
	v_or3_b32 v148, v147, v195, v236
	v_ldexp_f32 v146, v146, v149
	v_fmamk_f32 v146, v146, 0x31000000, v232
	v_rsq_f32_e32 v162, v146
	v_or3_b32 v146, v147, v196, v236
	v_lshlrev_b32_e32 v200, 2, v146
	v_lshlrev_b32_e32 v161, 2, v148
	v_pk_mul_f32 v[146:147], v[134:135], v[162:163] op_sel_hi:[1,0]
	v_pk_mul_f32 v[148:149], v[136:137], v[162:163] op_sel_hi:[1,0]
	s_nop 1
	v_mov_b32_dpp v163, v146 row_ror:2 row_mask:0xf bank_mask:0xf
	v_mov_b32_dpp v179, v146 row_ror:1 row_mask:0xf bank_mask:0xf
	v_mov_b32_dpp v181, v147 row_ror:1 row_mask:0xf bank_mask:0xf
	v_mov_b32_dpp v201, v147 row_ror:2 row_mask:0xf bank_mask:0xf
	v_mov_b32_dpp v183, v148 row_ror:1 row_mask:0xf bank_mask:0xf
	v_mov_b32_dpp v202, v148 row_ror:2 row_mask:0xf bank_mask:0xf
	v_mov_b32_dpp v185, v149 row_ror:1 row_mask:0xf bank_mask:0xf
	v_mov_b32_dpp v203, v149 row_ror:2 row_mask:0xf bank_mask:0xf
	s_waitcnt lgkmcnt(7)
	v_pk_mul_f32 v[136:137], v[144:145], v[162:163] op_sel_hi:[1,0]
	v_pk_mul_f32 v[134:135], v[142:143], v[162:163] op_sel_hi:[1,0]
	s_and_saveexec_b64 s[10:11], s[42:43]
	s_xor_b64 s[10:11], exec, s[10:11]
	s_movk_i32 s17, 0x2b00
	s_movk_i32 s84, 0x300
	s_mov_b32 s86, 0x24000
	s_mov_b32 s88, 0x48800000
	s_cbranch_execz .LBB0_43
	v_mov_b32_e32 v142, v149
	v_mov_b32_e32 v143, v141
	v_mov_b32_e32 v184, v133
	s_waitcnt lgkmcnt(1)
	v_pk_mul_f32 v[142:143], v[142:143], v[184:185]
	s_waitcnt lgkmcnt(0)
	v_fma_f32 v144, v117, v203, v121
	v_add_f32_e32 v143, v143, v144
	v_add_f32_e32 v142, v142, v143
	v_mul_f32_e32 v143, 0xbfb8aa3b, v142
	v_exp_f32_e32 v143, v143
	v_mov_b32_e32 v149, v140
	v_mov_b32_e32 v182, v132
	v_mov_b32_e32 v180, v131
	v_add_f32_e32 v143, 1.0, v143
	v_rcp_f32_e32 v143, v143
	v_mov_b32_e32 v178, v130
	v_mul_f32_e32 v142, v142, v143
	v_mul_f32_e32 v144, v137, v142
	v_pk_mul_f32 v[142:143], v[148:149], v[182:183]
	v_fma_f32 v137, v116, v202, v120
	v_add_f32_e32 v137, v143, v137
	v_add_f32_e32 v137, v142, v137
	v_mul_f32_e32 v142, 0xbfb8aa3b, v137
	v_exp_f32_e32 v142, v142
	v_fma_f32 v143, v115, v201, v119
	v_add_f32_e32 v142, 1.0, v142
	v_rcp_f32_e32 v142, v142
	s_nop 0
	v_mul_f32_e32 v137, v137, v142
	v_mul_f32_e32 v142, v136, v137
	v_mov_b32_e32 v136, v147
	v_mov_b32_e32 v137, v139
	v_pk_mul_f32 v[136:137], v[136:137], v[180:181]
	v_mov_b32_e32 v147, v138
	v_add_f32_e32 v137, v137, v143
	v_add_f32_e32 v136, v136, v137
	v_mul_f32_e32 v137, 0xbfb8aa3b, v136
	v_exp_f32_e32 v137, v137
	v_fma_f32 v143, v114, v163, v118
	v_add_f32_e32 v137, 1.0, v137
	v_rcp_f32_e32 v137, v137
	s_nop 0
	v_mul_f32_e32 v136, v136, v137
	v_mul_f32_e32 v135, v135, v136
	v_pk_mul_f32 v[136:137], v[146:147], v[178:179]
	s_nop 0
	v_add_f32_e32 v137, v137, v143
	v_add_f32_e32 v136, v136, v137
	v_mul_f32_e32 v137, 0xbfb8aa3b, v136
	v_exp_f32_e32 v137, v137
	s_nop 0
	v_add_f32_e32 v137, 1.0, v137
	v_rcp_f32_e32 v137, v137
	s_nop 0
	v_mul_f32_e32 v136, v136, v137
	v_mul_f32_e32 v134, v134, v136
	v_mov_b64_e32 v[136:137], s[48:49]
	v_mad_i64_i32 v[136:137], s[12:13], v160, s17, v[136:137]
	v_cvt_pk_bf16_f32 v134, v134, v135
	v_cvt_pk_bf16_f32 v135, v142, v144
	v_lshl_add_u64 v[136:137], v[156:157], 1, v[136:137]
	v_mov_b32_e32 v220, v134
	v_mov_b32_e32 v221, v135

; #define PG8_BAR __builtin_amdgcn_s_barrier()
; template <class Epi, class Sched, bool ALIGN_EPI = false, bool SP2 = false>
; __device__ __forceinline__ void gemm_phase(PG8_LAS unsigned char* lds, const Gemm g, const Sched& S, const Epi& E) {
;     ...
;         if constexpr (!Epi::AFTER_DRAIN) { E(acc, cur, wr, wc, fr, fq); S.done(cur); }
;         if (!has_next) break;
; #pragma unroll
;         for (int a = 0; a < 2; ++a)
; #pragma unroll
;             for (int b = 0; b < 2; ++b)
; #pragma unroll
;                 for (int m = 0; m < 4; ++m)
; #pragma unroll
;                     for (int n = 0; n < 2; ++n) acc[a][b][m][n] = (f32x4){0.f, 0.f, 0.f, 0.f};
;         cur = nxt; cA = nA; cB = nB; ++ui;
;         if constexpr (ALIGN_EPI) { if (wr == 1) PG8_BAR; }
;     }
.LBB0_65:
	s_or_b64 exec, exec, s[10:11]
	s_waitcnt vmcnt(16)
	s_andn2_b64 vcc, exec, s[46:47]
	s_mov_b64 s[10:11], -1
	s_cbranch_vccnz .LBB0_34
	s_andn2_b64 vcc, exec, s[22:23]
	s_cbranch_vccnz .LBB0_33
	s_barrier
	s_branch .LBB0_33
